# first LayerNorm phase also hand-written with next-row prefetch
# speedup vs baseline: 1.0039x; 1.0039x over previous
; DI void ln_row(const Ctx& c, int row, int l_post, int l_next, int lane) {
;   const Params& p = c.p;
;     const bool lat = row < MLAT;
;     const bool do_post = (l_post >= 0) && (lat || l_post <= 1);
;     const bool do_h = (l_next >= 0) && (lat || l_next <= 2);
;     if (!do_post && !do_h) return;
;     if (l_post >= 0 && !do_post) return;
;     const float* src = (l_post < 0) ? c.xin(row) : c.xrow(row);
;     float v[16];
; #pragma unroll
;     for (int i = 0; i < 4; ++i) { const float4 t = *(const float4*)(src + i * 256 + lane * 4); v[i * 4] = t.x; v[i * 4 + 1] = t.y; v[i * 4 + 2] = t.z; v[i * 4 + 3] = t.w; }
;     if (do_post) {
;       float s = 0.f;
; #pragma unroll
;       for (int i = 0; i < 16; ++i) s += v[i];
;       const float mean = wave_sum(s) * (1.f / D);
;       float q = 0.f;
; #pragma unroll
;       for (int i = 0; i < 16; ++i) { v[i] -= mean; q += v[i] * v[i]; }
;       const float rstd = rsqrtf(wave_sum(q) * (1.f / D) + LN_EPS);
;       float* dst = c.xrow(row);
; #pragma unroll
;       for (int i = 0; i < 4; ++i) {
;         const int col = i * 256 + lane * 4;
;         const float4 g = *(const float4*)(p.post_g + l_post * D + col), b = *(const float4*)(p.post_b + l_post * D + col);
;         v[i * 4] = v[i * 4] * rstd * g.x + b.x; v[i * 4 + 1] = v[i * 4 + 1] * rstd * g.y + b.y;
;         v[i * 4 + 2] = v[i * 4 + 2] * rstd * g.z + b.z; v[i * 4 + 3] = v[i * 4 + 3] * rstd * g.w + b.w;
;         *(float4*)(dst + col) = make_float4(v[i * 4], v[i * 4 + 1], v[i * 4 + 2], v[i * 4 + 3]);
;       }
;     }
;     if (do_h) {
;       float s = 0.f;
; #pragma unroll
;       for (int i = 0; i < 16; ++i) s += v[i];
;       const float mean = wave_sum(s) * (1.f / D);
;       float q = 0.f;
; #pragma unroll
;       for (int i = 0; i < 16; ++i) { v[i] -= mean; q += v[i] * v[i]; }
;       const float rstd = rsqrtf(wave_sum(q) * (1.f / D) + LN_EPS);
;       const float* md = c.MOD() + (l_next * 3 + mod_row(row)) * 3072;
;       bf16* dst = c.HY() + (size_t)row * D;
; DI void phase_ln(const Ctx& c, int l_post, int l_next) {
;   const int tid = otid(), lane = tid & 63;
;   const int wv = (blockIdx.x * NT + tid) >> 6, nw = (gridDim.x * NT) >> 6;
;   for (int row = wv; row < MT; row += 2 * nw) { ln_row(c, row, l_post, l_next, lane); if (row + nw < MT) ln_row(c, row + nw, l_post, l_next, lane); }
; }
.Lln0_entry:
	v_readlane_b32 s4, v252, 32
	v_lshrrev_b32_e32 v2, 6, v172
	s_nop 0
	v_readfirstlane_b32 s5, v2
	s_lshr_b32 s4, s4, 6
	s_add_i32 s6, s4, s5
	v_mbcnt_lo_u32_b32 v2, -1, 0
	v_mbcnt_hi_u32_b32 v2, -1, v2
	v_xor_b32_e32 v5, 16, v2
	v_lshlrev_b32_e32 v5, 2, v5
	v_lshlrev_b32_e32 v14, 3, v2
	v_lshlrev_b32_e32 v2, 4, v2
	s_mov_b64 s[30:31], s[44:45]
	s_mov_b64 s[28:29], s[48:49]
	s_mov_b32 s20, 0
	s_cmp_lt_u32 s6, 0x4000
	s_cbranch_scc0 .Lln0_c0
	s_lshl_b32 s2, s6, 12
	s_add_u32 s2, s30, s2
	s_addc_u32 s3, s31, 0
	s_lshr_b32 s8, s6, 13
	s_branch .Lln0_j0
.Lln0_c0:
	s_sub_u32 s2, s6, 0x4000
	s_lshl_b32 s2, s2, 12
	s_add_u32 s2, s28, s2
	s_addc_u32 s3, s29, 0
	s_mov_b32 s8, 2
.Lln0_j0:
	global_load_dwordx4 v[52:55], v2, s[2:3] offset:0
	global_load_dwordx4 v[56:59], v2, s[2:3] offset:1024
	global_load_dwordx4 v[60:63], v2, s[2:3] offset:2048
	global_load_dwordx4 v[64:67], v2, s[2:3] offset:3072
	s_add_u32 s8, s8, s20
	s_mul_i32 s8, s8, 0x3000
	s_add_u32 s10, s88, s8
	s_addc_u32 s11, s89, 0
	s_add_u32 s10, s10, 0x4000
	s_addc_u32 s11, s11, 0
	global_load_dwordx4 v[84:87], v2, s[10:11] offset:0
	global_load_dwordx4 v[88:91], v2, s[10:11] offset:1024
	global_load_dwordx4 v[92:95], v2, s[10:11] offset:2048
	global_load_dwordx4 v[96:99], v2, s[10:11] offset:3072
	s_add_u32 s10, s10, 0x1000
	s_addc_u32 s11, s11, 0
	global_load_dwordx4 v[100:103], v2, s[10:11] offset:0
	global_load_dwordx4 v[104:107], v2, s[10:11] offset:1024
	global_load_dwordx4 v[108:111], v2, s[10:11] offset:2048
	global_load_dwordx4 v[112:115], v2, s[10:11] offset:3072
.Lln0_loop:
	s_add_u32 s7, s6, 0x800
	s_cmp_lt_u32 s7, 0x4200
	s_cbranch_scc0 .Lln0_lastA
	s_cmp_lt_u32 s7, 0x4000
	s_cbranch_scc0 .Lln0_c1
	s_lshl_b32 s2, s7, 12
	s_add_u32 s2, s30, s2
	s_addc_u32 s3, s31, 0
	s_lshr_b32 s8, s7, 13
	s_branch .Lln0_j1
.Lln0_c1:
	s_sub_u32 s2, s7, 0x4000
	s_lshl_b32 s2, s2, 12
	s_add_u32 s2, s28, s2
	s_addc_u32 s3, s29, 0
	s_mov_b32 s8, 2
.Lln0_j1:
	global_load_dwordx4 v[68:71], v2, s[2:3] offset:0
	global_load_dwordx4 v[72:75], v2, s[2:3] offset:1024
	global_load_dwordx4 v[76:79], v2, s[2:3] offset:2048
	global_load_dwordx4 v[80:83], v2, s[2:3] offset:3072
	s_add_u32 s8, s8, s20
	s_mul_i32 s8, s8, 0x3000
	s_add_u32 s10, s88, s8
	s_addc_u32 s11, s89, 0
	s_add_u32 s10, s10, 0x4000
	s_addc_u32 s11, s11, 0
	global_load_dwordx4 v[116:119], v2, s[10:11] offset:0
	global_load_dwordx4 v[120:123], v2, s[10:11] offset:1024
	global_load_dwordx4 v[124:127], v2, s[10:11] offset:2048
	global_load_dwordx4 v[128:131], v2, s[10:11] offset:3072
	s_add_u32 s10, s10, 0x1000
	s_addc_u32 s11, s11, 0
	global_load_dwordx4 v[132:135], v2, s[10:11] offset:0
	global_load_dwordx4 v[136:139], v2, s[10:11] offset:1024
	global_load_dwordx4 v[140:143], v2, s[10:11] offset:2048
	global_load_dwordx4 v[144:147], v2, s[10:11] offset:3072
	s_waitcnt vmcnt(12)
	s_lshl_b32 s26, s6, 11
	s_add_u32 s26, s88, s26
	s_addc_u32 s27, s89, 0
	s_add_u32 s26, s26, 0x1128000
	s_addc_u32 s27, s27, 0
	v_add_f32_e32 v6, v52, v53
	v_add_f32_e32 v6, v6, v54
	v_add_f32_e32 v6, v6, v55
	v_add_f32_e32 v6, v6, v56
	v_add_f32_e32 v6, v6, v57
	v_add_f32_e32 v6, v6, v58
	v_add_f32_e32 v6, v6, v59
	v_add_f32_e32 v6, v6, v60
	v_add_f32_e32 v6, v6, v61
	v_add_f32_e32 v6, v6, v62
	v_add_f32_e32 v6, v6, v63
	v_add_f32_e32 v6, v6, v64
	v_add_f32_e32 v6, v6, v65
	v_add_f32_e32 v6, v6, v66
	v_add_f32_e32 v6, v6, v67
	s_nop 1
	v_add_f32_dpp v6, v6, v6 row_ror:8 row_mask:0xf bank_mask:0xf bound_ctrl:1
	s_nop 1
	v_add_f32_dpp v6, v6, v6 row_ror:4 row_mask:0xf bank_mask:0xf bound_ctrl:1
	s_nop 1
	v_add_f32_dpp v6, v6, v6 row_ror:2 row_mask:0xf bank_mask:0xf bound_ctrl:1
	s_nop 1
	v_add_f32_dpp v6, v6, v6 row_ror:1 row_mask:0xf bank_mask:0xf bound_ctrl:1
	ds_bpermute_b32 v8, v5, v6
	s_waitcnt lgkmcnt(0)
	v_add_f32_e32 v6, v6, v8
	v_mov_b32_e32 v8, v6
	s_nop 1
	v_permlane32_swap_b32_e32 v6, v8
	v_add_f32_e32 v6, v6, v8
	v_mul_f32_e32 v6, 0x3a800000, v6
	v_sub_f32_e32 v52, v52, v6
	v_sub_f32_e32 v53, v53, v6
	v_sub_f32_e32 v54, v54, v6
	v_sub_f32_e32 v55, v55, v6
	v_sub_f32_e32 v56, v56, v6
	v_sub_f32_e32 v57, v57, v6
	v_sub_f32_e32 v58, v58, v6
	v_sub_f32_e32 v59, v59, v6
	v_sub_f32_e32 v60, v60, v6
	v_sub_f32_e32 v61, v61, v6
	v_sub_f32_e32 v62, v62, v6
	v_sub_f32_e32 v63, v63, v6
	v_sub_f32_e32 v64, v64, v6
	v_sub_f32_e32 v65, v65, v6
	v_sub_f32_e32 v66, v66, v6
	v_sub_f32_e32 v67, v67, v6
	v_mul_f32_e32 v7, v52, v52
	v_fmac_f32_e32 v7, v53, v53
	v_fmac_f32_e32 v7, v54, v54
	v_fmac_f32_e32 v7, v55, v55
	v_fmac_f32_e32 v7, v56, v56
	v_fmac_f32_e32 v7, v57, v57
	v_fmac_f32_e32 v7, v58, v58
	v_fmac_f32_e32 v7, v59, v59
	v_fmac_f32_e32 v7, v60, v60
	v_fmac_f32_e32 v7, v61, v61
	v_fmac_f32_e32 v7, v62, v62
	v_fmac_f32_e32 v7, v63, v63
	v_fmac_f32_e32 v7, v64, v64
	v_fmac_f32_e32 v7, v65, v65
	v_fmac_f32_e32 v7, v66, v66
	v_fmac_f32_e32 v7, v67, v67
	s_nop 1
	v_add_f32_dpp v7, v7, v7 row_ror:8 row_mask:0xf bank_mask:0xf bound_ctrl:1
	s_nop 1
	v_add_f32_dpp v7, v7, v7 row_ror:4 row_mask:0xf bank_mask:0xf bound_ctrl:1
	s_nop 1
	v_add_f32_dpp v7, v7, v7 row_ror:2 row_mask:0xf bank_mask:0xf bound_ctrl:1
	s_nop 1
	v_add_f32_dpp v7, v7, v7 row_ror:1 row_mask:0xf bank_mask:0xf bound_ctrl:1
	ds_bpermute_b32 v8, v5, v7
	s_waitcnt lgkmcnt(0)
; DI bf16 f2bf(float f) { unsigned u = __float_as_uint(f); u += 0x7fffu + ((u >> 16) & 1u); return (bf16)(u >> 16); }
;   DI float* MOD() const { return (float*)(p.ws + WS_MOD); }
;   DI bf16* HY() const { return (bf16*)(p.ws + WS_HY); }
; DI void ln_row(const Ctx& c, int row, int l_post, int l_next, int lane) {
;     ...
;     if (do_h) {
;       float s = 0.f;
; #pragma unroll
;       for (int i = 0; i < 16; ++i) s += v[i];
;       const float mean = wave_sum(s) * (1.f / D);
;       float q = 0.f;
; #pragma unroll
;       for (int i = 0; i < 16; ++i) { v[i] -= mean; q += v[i] * v[i]; }
;       const float rstd = rsqrtf(wave_sum(q) * (1.f / D) + LN_EPS);
;       const float* md = c.MOD() + (l_next * 3 + mod_row(row)) * 3072;
;       bf16* dst = c.HY() + (size_t)row * D;
; #pragma unroll
;       for (int i = 0; i < 4; ++i) {
;         const int col = i * 256 + lane * 4;
;         const float4 sh = *(const float4*)(md + col), sc = *(const float4*)(md + 1024 + col);
;         const float h0 = v[i * 4] * rstd * (1.f + sc.x) + sh.x, h1 = v[i * 4 + 1] * rstd * (1.f + sc.y) + sh.y;
;         const float h2 = v[i * 4 + 2] * rstd * (1.f + sc.z) + sh.z, h3 = v[i * 4 + 3] * rstd * (1.f + sc.w) + sh.w;
;         uint2 pk; pk.x = (unsigned)f2bf(h0) | ((unsigned)f2bf(h1) << 16); pk.y = (unsigned)f2bf(h2) | ((unsigned)f2bf(h3) << 16);
;         *(uint2*)(dst + col) = pk;
;       }
	v_add_f32_e32 v7, v7, v8
	v_mov_b32_e32 v8, v7
	s_nop 1
	v_permlane32_swap_b32_e32 v7, v8
	v_add_f32_e32 v7, v7, v8
	v_mov_b32_e32 v8, 0x358637bd
	v_fmac_f32_e32 v8, 0x3a800000, v7
	v_rsq_f32_e32 v7, v8
	s_nop 0
	v_mul_f32_e32 v52, v52, v7
	v_mul_f32_e32 v53, v53, v7
	v_mul_f32_e32 v54, v54, v7
	v_mul_f32_e32 v55, v55, v7
	v_mul_f32_e32 v56, v56, v7
	v_mul_f32_e32 v57, v57, v7
	v_mul_f32_e32 v58, v58, v7
	v_mul_f32_e32 v59, v59, v7
	v_mul_f32_e32 v60, v60, v7
	v_mul_f32_e32 v61, v61, v7
	v_mul_f32_e32 v62, v62, v7
	v_mul_f32_e32 v63, v63, v7
	v_mul_f32_e32 v64, v64, v7
	v_mul_f32_e32 v65, v65, v7
	v_mul_f32_e32 v66, v66, v7
	v_mul_f32_e32 v67, v67, v7
	v_add_f32_e32 v100, 1.0, v100
	v_add_f32_e32 v101, 1.0, v101
	v_add_f32_e32 v102, 1.0, v102
	v_add_f32_e32 v103, 1.0, v103
	v_add_f32_e32 v104, 1.0, v104
	v_add_f32_e32 v105, 1.0, v105
	v_add_f32_e32 v106, 1.0, v106
	v_add_f32_e32 v107, 1.0, v107
	v_add_f32_e32 v108, 1.0, v108
	v_add_f32_e32 v109, 1.0, v109
	v_add_f32_e32 v110, 1.0, v110
	v_add_f32_e32 v111, 1.0, v111
	v_add_f32_e32 v112, 1.0, v112
	v_add_f32_e32 v113, 1.0, v113
	v_add_f32_e32 v114, 1.0, v114
	v_add_f32_e32 v115, 1.0, v115
	v_fma_f32 v52, v52, v100, v84
	v_fma_f32 v53, v53, v101, v85
	v_fma_f32 v54, v54, v102, v86
	v_fma_f32 v55, v55, v103, v87
	v_fma_f32 v56, v56, v104, v88
	v_fma_f32 v57, v57, v105, v89
	v_fma_f32 v58, v58, v106, v90
	v_fma_f32 v59, v59, v107, v91
	v_fma_f32 v60, v60, v108, v92
	v_fma_f32 v61, v61, v109, v93
	v_fma_f32 v62, v62, v110, v94
	v_fma_f32 v63, v63, v111, v95
	v_fma_f32 v64, v64, v112, v96
	v_fma_f32 v65, v65, v113, v97
	v_fma_f32 v66, v66, v114, v98
	v_fma_f32 v67, v67, v115, v99
	v_cvt_pk_bf16_f32 v52, v52, v53
	v_cvt_pk_bf16_f32 v53, v54, v55
	v_cvt_pk_bf16_f32 v54, v56, v57
	v_cvt_pk_bf16_f32 v55, v58, v59
	v_cvt_pk_bf16_f32 v56, v60, v61
	v_cvt_pk_bf16_f32 v57, v62, v63
	v_cvt_pk_bf16_f32 v58, v64, v65
	v_cvt_pk_bf16_f32 v59, v66, v67
	global_store_dwordx2 v14, v[52:53], s[26:27] offset:0
	global_store_dwordx2 v14, v[54:55], s[26:27] offset:512
	global_store_dwordx2 v14, v[56:57], s[26:27] offset:1024
	global_store_dwordx2 v14, v[58:59], s[26:27] offset:1536
	s_mov_b32 s6, s7
	s_branch .Lln0_nextB
.Lln0_lastA:
	s_waitcnt vmcnt(0)
	s_lshl_b32 s26, s6, 11
	s_add_u32 s26, s88, s26
	s_addc_u32 s27, s89, 0
	s_add_u32 s26, s26, 0x1128000
	s_addc_u32 s27, s27, 0
	v_add_f32_e32 v6, v52, v53
	v_add_f32_e32 v6, v6, v54
	v_add_f32_e32 v6, v6, v55
	v_add_f32_e32 v6, v6, v56
	v_add_f32_e32 v6, v6, v57
	v_add_f32_e32 v6, v6, v58
	v_add_f32_e32 v6, v6, v59
	v_add_f32_e32 v6, v6, v60
	v_add_f32_e32 v6, v6, v61
	v_add_f32_e32 v6, v6, v62
	v_add_f32_e32 v6, v6, v63
	v_add_f32_e32 v6, v6, v64
	v_add_f32_e32 v6, v6, v65
	v_add_f32_e32 v6, v6, v66
	v_add_f32_e32 v6, v6, v67
	s_nop 1
	v_add_f32_dpp v6, v6, v6 row_ror:8 row_mask:0xf bank_mask:0xf bound_ctrl:1
	s_nop 1
	v_add_f32_dpp v6, v6, v6 row_ror:4 row_mask:0xf bank_mask:0xf bound_ctrl:1
	s_nop 1
	v_add_f32_dpp v6, v6, v6 row_ror:2 row_mask:0xf bank_mask:0xf bound_ctrl:1
	s_nop 1
	v_add_f32_dpp v6, v6, v6 row_ror:1 row_mask:0xf bank_mask:0xf bound_ctrl:1
	ds_bpermute_b32 v8, v5, v6
	s_waitcnt lgkmcnt(0)
	v_add_f32_e32 v6, v6, v8
	v_mov_b32_e32 v8, v6
	s_nop 1
	v_permlane32_swap_b32_e32 v6, v8
	v_add_f32_e32 v6, v6, v8
	v_mul_f32_e32 v6, 0x3a800000, v6
	v_sub_f32_e32 v52, v52, v6
	v_sub_f32_e32 v53, v53, v6
	v_sub_f32_e32 v54, v54, v6
	v_sub_f32_e32 v55, v55, v6
	v_sub_f32_e32 v56, v56, v6
	v_sub_f32_e32 v57, v57, v6
	v_sub_f32_e32 v58, v58, v6
	v_sub_f32_e32 v59, v59, v6
	v_sub_f32_e32 v60, v60, v6
	v_sub_f32_e32 v61, v61, v6
	v_sub_f32_e32 v62, v62, v6
	v_sub_f32_e32 v63, v63, v6
	v_sub_f32_e32 v64, v64, v6
	v_sub_f32_e32 v65, v65, v6
	v_sub_f32_e32 v66, v66, v6
	v_sub_f32_e32 v67, v67, v6
	v_mul_f32_e32 v7, v52, v52
	v_fmac_f32_e32 v7, v53, v53
	v_fmac_f32_e32 v7, v54, v54
	v_fmac_f32_e32 v7, v55, v55
	v_fmac_f32_e32 v7, v56, v56
	v_fmac_f32_e32 v7, v57, v57
	v_fmac_f32_e32 v7, v58, v58
	v_fmac_f32_e32 v7, v59, v59
	v_fmac_f32_e32 v7, v60, v60
	v_fmac_f32_e32 v7, v61, v61
	v_fmac_f32_e32 v7, v62, v62
	v_fmac_f32_e32 v7, v63, v63
	v_fmac_f32_e32 v7, v64, v64
	v_fmac_f32_e32 v7, v65, v65
	v_fmac_f32_e32 v7, v66, v66
	v_fmac_f32_e32 v7, v67, v67
	s_nop 1
	v_add_f32_dpp v7, v7, v7 row_ror:8 row_mask:0xf bank_mask:0xf bound_ctrl:1
	s_nop 1
	v_add_f32_dpp v7, v7, v7 row_ror:4 row_mask:0xf bank_mask:0xf bound_ctrl:1
	s_nop 1
	v_add_f32_dpp v7, v7, v7 row_ror:2 row_mask:0xf bank_mask:0xf bound_ctrl:1
	s_nop 1
	v_add_f32_dpp v7, v7, v7 row_ror:1 row_mask:0xf bank_mask:0xf bound_ctrl:1
	ds_bpermute_b32 v8, v5, v7
	s_waitcnt lgkmcnt(0)
	v_add_f32_e32 v7, v7, v8
	v_mov_b32_e32 v8, v7
	s_nop 1
	v_permlane32_swap_b32_e32 v7, v8
	v_add_f32_e32 v7, v7, v8
	v_mov_b32_e32 v8, 0x358637bd
	v_fmac_f32_e32 v8, 0x3a800000, v7
	v_rsq_f32_e32 v7, v8
	s_nop 0
	v_mul_f32_e32 v52, v52, v7
	v_mul_f32_e32 v53, v53, v7
	v_mul_f32_e32 v54, v54, v7
	v_mul_f32_e32 v55, v55, v7
	v_mul_f32_e32 v56, v56, v7
	v_mul_f32_e32 v57, v57, v7
	v_mul_f32_e32 v58, v58, v7
	v_mul_f32_e32 v59, v59, v7
	v_mul_f32_e32 v60, v60, v7
	v_mul_f32_e32 v61, v61, v7
	v_mul_f32_e32 v62, v62, v7
	v_mul_f32_e32 v63, v63, v7
	v_mul_f32_e32 v64, v64, v7
	v_mul_f32_e32 v65, v65, v7
	v_mul_f32_e32 v66, v66, v7
	v_mul_f32_e32 v67, v67, v7
	v_add_f32_e32 v100, 1.0, v100
	v_add_f32_e32 v101, 1.0, v101
	v_add_f32_e32 v102, 1.0, v102
	v_add_f32_e32 v103, 1.0, v103
	v_add_f32_e32 v104, 1.0, v104
	v_add_f32_e32 v105, 1.0, v105
	v_add_f32_e32 v106, 1.0, v106
	v_add_f32_e32 v107, 1.0, v107
	v_add_f32_e32 v108, 1.0, v108
	v_add_f32_e32 v109, 1.0, v109
	v_add_f32_e32 v110, 1.0, v110
	v_add_f32_e32 v111, 1.0, v111
	v_add_f32_e32 v112, 1.0, v112
	v_add_f32_e32 v113, 1.0, v113
	v_add_f32_e32 v114, 1.0, v114
	v_add_f32_e32 v115, 1.0, v115
	v_fma_f32 v52, v52, v100, v84
	v_fma_f32 v53, v53, v101, v85
	v_fma_f32 v54, v54, v102, v86
	v_fma_f32 v55, v55, v103, v87
	v_fma_f32 v56, v56, v104, v88
	v_fma_f32 v57, v57, v105, v89
	v_fma_f32 v58, v58, v106, v90
	v_fma_f32 v59, v59, v107, v91
	v_fma_f32 v60, v60, v108, v92
	v_fma_f32 v61, v61, v109, v93
	v_fma_f32 v62, v62, v110, v94
	v_fma_f32 v63, v63, v111, v95
	v_fma_f32 v64, v64, v112, v96
	v_fma_f32 v65, v65, v113, v97
	v_fma_f32 v66, v66, v114, v98
	v_fma_f32 v67, v67, v115, v99
	v_cvt_pk_bf16_f32 v52, v52, v53
	v_cvt_pk_bf16_f32 v53, v54, v55
	v_cvt_pk_bf16_f32 v54, v56, v57
	v_cvt_pk_bf16_f32 v55, v58, v59
	v_cvt_pk_bf16_f32 v56, v60, v61
	v_cvt_pk_bf16_f32 v57, v62, v63
	v_cvt_pk_bf16_f32 v58, v64, v65
	v_cvt_pk_bf16_f32 v59, v66, v67
	global_store_dwordx2 v14, v[52:53], s[26:27] offset:0
	global_store_dwordx2 v14, v[54:55], s[26:27] offset:512
	global_store_dwordx2 v14, v[56:57], s[26:27] offset:1024
	global_store_dwordx2 v14, v[58:59], s[26:27] offset:1536
	s_branch .Lln0_exit

; DI bf16 f2bf(float f) { unsigned u = __float_as_uint(f); u += 0x7fffu + ((u >> 16) & 1u); return (bf16)(u >> 16); }
;   DI float* MOD() const { return (float*)(p.ws + WS_MOD); }
;   DI bf16* HY() const { return (bf16*)(p.ws + WS_HY); }
;   DI float* xrow(int row) const { return row < MLAT ? p.out + (size_t)row * D : XC() + (size_t)(row - MLAT) * D; }
; DI void ln_row(const Ctx& c, int row, int l_post, int l_next, int lane) {
;     ...
;     const float* src = (l_post < 0) ? c.xin(row) : c.xrow(row);
;     float v[16];
; #pragma unroll
;     for (int i = 0; i < 4; ++i) { const float4 t = *(const float4*)(src + i * 256 + lane * 4); v[i * 4] = t.x; v[i * 4 + 1] = t.y; v[i * 4 + 2] = t.z; v[i * 4 + 3] = t.w; }
;     ...
;     if (do_h) {
;       float s = 0.f;
; #pragma unroll
;       for (int i = 0; i < 16; ++i) s += v[i];
;       const float mean = wave_sum(s) * (1.f / D);
;       float q = 0.f;
; #pragma unroll
;       for (int i = 0; i < 16; ++i) { v[i] -= mean; q += v[i] * v[i]; }
;       const float rstd = rsqrtf(wave_sum(q) * (1.f / D) + LN_EPS);
;       const float* md = c.MOD() + (l_next * 3 + mod_row(row)) * 3072;
;       bf16* dst = c.HY() + (size_t)row * D;
; #pragma unroll
;       for (int i = 0; i < 4; ++i) {
;         const int col = i * 256 + lane * 4;
;         const float4 sh = *(const float4*)(md + col), sc = *(const float4*)(md + 1024 + col);
;         const float h0 = v[i * 4] * rstd * (1.f + sc.x) + sh.x, h1 = v[i * 4 + 1] * rstd * (1.f + sc.y) + sh.y;
;         const float h2 = v[i * 4 + 2] * rstd * (1.f + sc.z) + sh.z, h3 = v[i * 4 + 3] * rstd * (1.f + sc.w) + sh.w;
;         uint2 pk; pk.x = (unsigned)f2bf(h0) | ((unsigned)f2bf(h1) << 16); pk.y = (unsigned)f2bf(h2) | ((unsigned)f2bf(h3) << 16);
;         *(uint2*)(dst + col) = pk;
;       }
.Lln0_j2:
	global_load_dwordx4 v[52:55], v2, s[2:3] offset:0
	global_load_dwordx4 v[56:59], v2, s[2:3] offset:1024
	global_load_dwordx4 v[60:63], v2, s[2:3] offset:2048
	global_load_dwordx4 v[64:67], v2, s[2:3] offset:3072
	s_add_u32 s8, s8, s20
	s_mul_i32 s8, s8, 0x3000
	s_add_u32 s10, s88, s8
	s_addc_u32 s11, s89, 0
	s_add_u32 s10, s10, 0x4000
	s_addc_u32 s11, s11, 0
	global_load_dwordx4 v[84:87], v2, s[10:11] offset:0
	global_load_dwordx4 v[88:91], v2, s[10:11] offset:1024
	global_load_dwordx4 v[92:95], v2, s[10:11] offset:2048
	global_load_dwordx4 v[96:99], v2, s[10:11] offset:3072
	s_add_u32 s10, s10, 0x1000
	s_addc_u32 s11, s11, 0
	global_load_dwordx4 v[100:103], v2, s[10:11] offset:0
	global_load_dwordx4 v[104:107], v2, s[10:11] offset:1024
	global_load_dwordx4 v[108:111], v2, s[10:11] offset:2048
	global_load_dwordx4 v[112:115], v2, s[10:11] offset:3072
	s_waitcnt vmcnt(12)
	s_lshl_b32 s26, s6, 11
	s_add_u32 s26, s88, s26
	s_addc_u32 s27, s89, 0
	s_add_u32 s26, s26, 0x1128000
	s_addc_u32 s27, s27, 0
	v_add_f32_e32 v6, v68, v69
	v_add_f32_e32 v6, v6, v70
	v_add_f32_e32 v6, v6, v71
	v_add_f32_e32 v6, v6, v72
	v_add_f32_e32 v6, v6, v73
	v_add_f32_e32 v6, v6, v74
	v_add_f32_e32 v6, v6, v75
	v_add_f32_e32 v6, v6, v76
	v_add_f32_e32 v6, v6, v77
	v_add_f32_e32 v6, v6, v78
	v_add_f32_e32 v6, v6, v79
	v_add_f32_e32 v6, v6, v80
	v_add_f32_e32 v6, v6, v81
	v_add_f32_e32 v6, v6, v82
	v_add_f32_e32 v6, v6, v83
	s_nop 1
	v_add_f32_dpp v6, v6, v6 row_ror:8 row_mask:0xf bank_mask:0xf bound_ctrl:1
	s_nop 1
	v_add_f32_dpp v6, v6, v6 row_ror:4 row_mask:0xf bank_mask:0xf bound_ctrl:1
	s_nop 1
	v_add_f32_dpp v6, v6, v6 row_ror:2 row_mask:0xf bank_mask:0xf bound_ctrl:1
	s_nop 1
	v_add_f32_dpp v6, v6, v6 row_ror:1 row_mask:0xf bank_mask:0xf bound_ctrl:1
	ds_bpermute_b32 v8, v5, v6
	s_waitcnt lgkmcnt(0)
	v_add_f32_e32 v6, v6, v8
	v_mov_b32_e32 v8, v6
	s_nop 1
	v_permlane32_swap_b32_e32 v6, v8
	v_add_f32_e32 v6, v6, v8
	v_mul_f32_e32 v6, 0x3a800000, v6
	v_sub_f32_e32 v68, v68, v6
	v_sub_f32_e32 v69, v69, v6
	v_sub_f32_e32 v70, v70, v6
	v_sub_f32_e32 v71, v71, v6
	v_sub_f32_e32 v72, v72, v6
	v_sub_f32_e32 v73, v73, v6
	v_sub_f32_e32 v74, v74, v6
	v_sub_f32_e32 v75, v75, v6
	v_sub_f32_e32 v76, v76, v6
	v_sub_f32_e32 v77, v77, v6
	v_sub_f32_e32 v78, v78, v6
	v_sub_f32_e32 v79, v79, v6
	v_sub_f32_e32 v80, v80, v6
	v_sub_f32_e32 v81, v81, v6
	v_sub_f32_e32 v82, v82, v6
	v_sub_f32_e32 v83, v83, v6
	v_mul_f32_e32 v7, v68, v68
	v_fmac_f32_e32 v7, v69, v69
	v_fmac_f32_e32 v7, v70, v70
	v_fmac_f32_e32 v7, v71, v71
	v_fmac_f32_e32 v7, v72, v72
	v_fmac_f32_e32 v7, v73, v73
	v_fmac_f32_e32 v7, v74, v74
	v_fmac_f32_e32 v7, v75, v75
	v_fmac_f32_e32 v7, v76, v76
	v_fmac_f32_e32 v7, v77, v77
	v_fmac_f32_e32 v7, v78, v78
	v_fmac_f32_e32 v7, v79, v79
	v_fmac_f32_e32 v7, v80, v80
	v_fmac_f32_e32 v7, v81, v81
	v_fmac_f32_e32 v7, v82, v82
	v_fmac_f32_e32 v7, v83, v83
	s_nop 1
	v_add_f32_dpp v7, v7, v7 row_ror:8 row_mask:0xf bank_mask:0xf bound_ctrl:1
	s_nop 1
	v_add_f32_dpp v7, v7, v7 row_ror:4 row_mask:0xf bank_mask:0xf bound_ctrl:1
	s_nop 1
	v_add_f32_dpp v7, v7, v7 row_ror:2 row_mask:0xf bank_mask:0xf bound_ctrl:1
	s_nop 1
	v_add_f32_dpp v7, v7, v7 row_ror:1 row_mask:0xf bank_mask:0xf bound_ctrl:1
	ds_bpermute_b32 v8, v5, v7
	s_waitcnt lgkmcnt(0)
	v_add_f32_e32 v7, v7, v8
	v_mov_b32_e32 v8, v7
	s_nop 1
	v_permlane32_swap_b32_e32 v7, v8
	v_add_f32_e32 v7, v7, v8
	v_mov_b32_e32 v8, 0x358637bd
	v_fmac_f32_e32 v8, 0x3a800000, v7
	v_rsq_f32_e32 v7, v8
	s_nop 0
	v_mul_f32_e32 v68, v68, v7
	v_mul_f32_e32 v69, v69, v7
	v_mul_f32_e32 v70, v70, v7
	v_mul_f32_e32 v71, v71, v7
	v_mul_f32_e32 v72, v72, v7
	v_mul_f32_e32 v73, v73, v7
	v_mul_f32_e32 v74, v74, v7
	v_mul_f32_e32 v75, v75, v7
	v_mul_f32_e32 v76, v76, v7
	v_mul_f32_e32 v77, v77, v7
	v_mul_f32_e32 v78, v78, v7
	v_mul_f32_e32 v79, v79, v7
	v_mul_f32_e32 v80, v80, v7
	v_mul_f32_e32 v81, v81, v7
	v_mul_f32_e32 v82, v82, v7
	v_mul_f32_e32 v83, v83, v7
	v_add_f32_e32 v132, 1.0, v132
	v_add_f32_e32 v133, 1.0, v133
	v_add_f32_e32 v134, 1.0, v134
	v_add_f32_e32 v135, 1.0, v135
	v_add_f32_e32 v136, 1.0, v136
	v_add_f32_e32 v137, 1.0, v137
	v_add_f32_e32 v138, 1.0, v138
	v_add_f32_e32 v139, 1.0, v139
	v_add_f32_e32 v140, 1.0, v140
	v_add_f32_e32 v141, 1.0, v141
	v_add_f32_e32 v142, 1.0, v142
	v_add_f32_e32 v143, 1.0, v143
	v_add_f32_e32 v144, 1.0, v144
	v_add_f32_e32 v145, 1.0, v145
	v_add_f32_e32 v146, 1.0, v146
	v_add_f32_e32 v147, 1.0, v147
	v_fma_f32 v68, v68, v132, v116
	v_fma_f32 v69, v69, v133, v117
	v_fma_f32 v70, v70, v134, v118
	v_fma_f32 v71, v71, v135, v119
	v_fma_f32 v72, v72, v136, v120
	v_fma_f32 v73, v73, v137, v121
	v_fma_f32 v74, v74, v138, v122
	v_fma_f32 v75, v75, v139, v123
	v_fma_f32 v76, v76, v140, v124
	v_fma_f32 v77, v77, v141, v125
	v_fma_f32 v78, v78, v142, v126
	v_fma_f32 v79, v79, v143, v127
	v_fma_f32 v80, v80, v144, v128
	v_fma_f32 v81, v81, v145, v129
	v_fma_f32 v82, v82, v146, v130
	v_fma_f32 v83, v83, v147, v131
	v_cvt_pk_bf16_f32 v68, v68, v69
	v_cvt_pk_bf16_f32 v69, v70, v71
	v_cvt_pk_bf16_f32 v70, v72, v73
	v_cvt_pk_bf16_f32 v71, v74, v75
	v_cvt_pk_bf16_f32 v72, v76, v77
	v_cvt_pk_bf16_f32 v73, v78, v79
	v_cvt_pk_bf16_f32 v74, v80, v81
	v_cvt_pk_bf16_f32 v75, v82, v83
	global_store_dwordx2 v14, v[68:69], s[26:27] offset:0
	global_store_dwordx2 v14, v[70:71], s[26:27] offset:512
	global_store_dwordx2 v14, v[72:73], s[26:27] offset:1024
	global_store_dwordx2 v14, v[74:75], s[26:27] offset:1536
	s_mov_b32 s6, s7
	s_branch .Lln0_loop
; DI bf16 f2bf(float f) { unsigned u = __float_as_uint(f); u += 0x7fffu + ((u >> 16) & 1u); return (bf16)(u >> 16); }
;   DI float* MOD() const { return (float*)(p.ws + WS_MOD); }
;   DI bf16* HY() const { return (bf16*)(p.ws + WS_HY); }
; DI unsigned xb_add(unsigned* p, unsigned v) { return __hip_atomic_fetch_add(p, v, __ATOMIC_RELAXED, __HIP_MEMORY_SCOPE_AGENT); }
; DI void ln_row(const Ctx& c, int row, int l_post, int l_next, int lane) {
;     ...
;     if (do_h) {
;       float s = 0.f;
; #pragma unroll
;       for (int i = 0; i < 16; ++i) s += v[i];
;       const float mean = wave_sum(s) * (1.f / D);
;       float q = 0.f;
; #pragma unroll
;       for (int i = 0; i < 16; ++i) { v[i] -= mean; q += v[i] * v[i]; }
;       const float rstd = rsqrtf(wave_sum(q) * (1.f / D) + LN_EPS);
;       const float* md = c.MOD() + (l_next * 3 + mod_row(row)) * 3072;
;       bf16* dst = c.HY() + (size_t)row * D;
; #pragma unroll
;       for (int i = 0; i < 4; ++i) {
;         const int col = i * 256 + lane * 4;
;         const float4 sh = *(const float4*)(md + col), sc = *(const float4*)(md + 1024 + col);
;         const float h0 = v[i * 4] * rstd * (1.f + sc.x) + sh.x, h1 = v[i * 4 + 1] * rstd * (1.f + sc.y) + sh.y;
;         const float h2 = v[i * 4 + 2] * rstd * (1.f + sc.z) + sh.z, h3 = v[i * 4 + 3] * rstd * (1.f + sc.w) + sh.w;
;         uint2 pk; pk.x = (unsigned)f2bf(h0) | ((unsigned)f2bf(h1) << 16); pk.y = (unsigned)f2bf(h2) | ((unsigned)f2bf(h3) << 16);
;         *(uint2*)(dst + col) = pk;
;       }
; DI void xcd_barrier(const XcdBarrier& b) {
;   asm volatile("s_waitcnt vmcnt(0)" ::: "memory");
;   __syncthreads();
;   if (threadIdx.x == 0) {
;     unsigned* bar = b.bar;
;     __builtin_amdgcn_s_waitcnt(0);
;     unsigned nloc = b.st[0], nx = b.st[1];
;     if (nloc == 0u) { xcd_barrier_complete(bar, b.x, nloc, nx); b.st[0] = nloc; b.st[1] = nx; }
;     const unsigned old = xb_add(&bar[XB_XSUB(b.x)], 1u);
;     const unsigned gen = old / nloc;
;     if (old + 1u == (gen + 1u) * nloc) {
.Lln0_lastB:
	s_waitcnt vmcnt(0)
	s_lshl_b32 s26, s6, 11
	s_add_u32 s26, s88, s26
	s_addc_u32 s27, s89, 0
	s_add_u32 s26, s26, 0x1128000
	s_addc_u32 s27, s27, 0
	v_add_f32_e32 v6, v68, v69
	v_add_f32_e32 v6, v6, v70
	v_add_f32_e32 v6, v6, v71
	v_add_f32_e32 v6, v6, v72
	v_add_f32_e32 v6, v6, v73
	v_add_f32_e32 v6, v6, v74
	v_add_f32_e32 v6, v6, v75
	v_add_f32_e32 v6, v6, v76
	v_add_f32_e32 v6, v6, v77
	v_add_f32_e32 v6, v6, v78
	v_add_f32_e32 v6, v6, v79
	v_add_f32_e32 v6, v6, v80
	v_add_f32_e32 v6, v6, v81
	v_add_f32_e32 v6, v6, v82
	v_add_f32_e32 v6, v6, v83
	s_nop 1
	v_add_f32_dpp v6, v6, v6 row_ror:8 row_mask:0xf bank_mask:0xf bound_ctrl:1
	s_nop 1
	v_add_f32_dpp v6, v6, v6 row_ror:4 row_mask:0xf bank_mask:0xf bound_ctrl:1
	s_nop 1
	v_add_f32_dpp v6, v6, v6 row_ror:2 row_mask:0xf bank_mask:0xf bound_ctrl:1
	s_nop 1
	v_add_f32_dpp v6, v6, v6 row_ror:1 row_mask:0xf bank_mask:0xf bound_ctrl:1
	ds_bpermute_b32 v8, v5, v6
	s_waitcnt lgkmcnt(0)
	v_add_f32_e32 v6, v6, v8
	v_mov_b32_e32 v8, v6
	s_nop 1
	v_permlane32_swap_b32_e32 v6, v8
	v_add_f32_e32 v6, v6, v8
	v_mul_f32_e32 v6, 0x3a800000, v6
	v_sub_f32_e32 v68, v68, v6
	v_sub_f32_e32 v69, v69, v6
	v_sub_f32_e32 v70, v70, v6
	v_sub_f32_e32 v71, v71, v6
	v_sub_f32_e32 v72, v72, v6
	v_sub_f32_e32 v73, v73, v6
	v_sub_f32_e32 v74, v74, v6
	v_sub_f32_e32 v75, v75, v6
	v_sub_f32_e32 v76, v76, v6
	v_sub_f32_e32 v77, v77, v6
	v_sub_f32_e32 v78, v78, v6
	v_sub_f32_e32 v79, v79, v6
	v_sub_f32_e32 v80, v80, v6
	v_sub_f32_e32 v81, v81, v6
	v_sub_f32_e32 v82, v82, v6
	v_sub_f32_e32 v83, v83, v6
	v_mul_f32_e32 v7, v68, v68
	v_fmac_f32_e32 v7, v69, v69
	v_fmac_f32_e32 v7, v70, v70
	v_fmac_f32_e32 v7, v71, v71
	v_fmac_f32_e32 v7, v72, v72
	v_fmac_f32_e32 v7, v73, v73
	v_fmac_f32_e32 v7, v74, v74
	v_fmac_f32_e32 v7, v75, v75
	v_fmac_f32_e32 v7, v76, v76
	v_fmac_f32_e32 v7, v77, v77
	v_fmac_f32_e32 v7, v78, v78
	v_fmac_f32_e32 v7, v79, v79
	v_fmac_f32_e32 v7, v80, v80
	v_fmac_f32_e32 v7, v81, v81
	v_fmac_f32_e32 v7, v82, v82
	v_fmac_f32_e32 v7, v83, v83
	s_nop 1
	v_add_f32_dpp v7, v7, v7 row_ror:8 row_mask:0xf bank_mask:0xf bound_ctrl:1
	s_nop 1
	v_add_f32_dpp v7, v7, v7 row_ror:4 row_mask:0xf bank_mask:0xf bound_ctrl:1
	s_nop 1
	v_add_f32_dpp v7, v7, v7 row_ror:2 row_mask:0xf bank_mask:0xf bound_ctrl:1
	s_nop 1
	v_add_f32_dpp v7, v7, v7 row_ror:1 row_mask:0xf bank_mask:0xf bound_ctrl:1
	ds_bpermute_b32 v8, v5, v7
	s_waitcnt lgkmcnt(0)
	v_add_f32_e32 v7, v7, v8
	v_mov_b32_e32 v8, v7
	s_nop 1
	v_permlane32_swap_b32_e32 v7, v8
	v_add_f32_e32 v7, v7, v8
	v_mov_b32_e32 v8, 0x358637bd
	v_fmac_f32_e32 v8, 0x3a800000, v7
	v_rsq_f32_e32 v7, v8
	s_nop 0
	v_mul_f32_e32 v68, v68, v7
	v_mul_f32_e32 v69, v69, v7
	v_mul_f32_e32 v70, v70, v7
	v_mul_f32_e32 v71, v71, v7
	v_mul_f32_e32 v72, v72, v7
	v_mul_f32_e32 v73, v73, v7
	v_mul_f32_e32 v74, v74, v7
	v_mul_f32_e32 v75, v75, v7
	v_mul_f32_e32 v76, v76, v7
	v_mul_f32_e32 v77, v77, v7
	v_mul_f32_e32 v78, v78, v7
	v_mul_f32_e32 v79, v79, v7
	v_mul_f32_e32 v80, v80, v7
	v_mul_f32_e32 v81, v81, v7
	v_mul_f32_e32 v82, v82, v7
	v_mul_f32_e32 v83, v83, v7
	v_add_f32_e32 v132, 1.0, v132
	v_add_f32_e32 v133, 1.0, v133
	v_add_f32_e32 v134, 1.0, v134
	v_add_f32_e32 v135, 1.0, v135
	v_add_f32_e32 v136, 1.0, v136
	v_add_f32_e32 v137, 1.0, v137
	v_add_f32_e32 v138, 1.0, v138
	v_add_f32_e32 v139, 1.0, v139
	v_add_f32_e32 v140, 1.0, v140
	v_add_f32_e32 v141, 1.0, v141
	v_add_f32_e32 v142, 1.0, v142
	v_add_f32_e32 v143, 1.0, v143
	v_add_f32_e32 v144, 1.0, v144
	v_add_f32_e32 v145, 1.0, v145
	v_add_f32_e32 v146, 1.0, v146
	v_add_f32_e32 v147, 1.0, v147
	v_fma_f32 v68, v68, v132, v116
	v_fma_f32 v69, v69, v133, v117
	v_fma_f32 v70, v70, v134, v118
	v_fma_f32 v71, v71, v135, v119
	v_fma_f32 v72, v72, v136, v120
	v_fma_f32 v73, v73, v137, v121
	v_fma_f32 v74, v74, v138, v122
	v_fma_f32 v75, v75, v139, v123
	v_fma_f32 v76, v76, v140, v124
	v_fma_f32 v77, v77, v141, v125
	v_fma_f32 v78, v78, v142, v126
	v_fma_f32 v79, v79, v143, v127
	v_fma_f32 v80, v80, v144, v128
	v_fma_f32 v81, v81, v145, v129
	v_fma_f32 v82, v82, v146, v130
	v_fma_f32 v83, v83, v147, v131
	v_cvt_pk_bf16_f32 v68, v68, v69
	v_cvt_pk_bf16_f32 v69, v70, v71
	v_cvt_pk_bf16_f32 v70, v72, v73
	v_cvt_pk_bf16_f32 v71, v74, v75
	v_cvt_pk_bf16_f32 v72, v76, v77
	v_cvt_pk_bf16_f32 v73, v78, v79
	v_cvt_pk_bf16_f32 v74, v80, v81
	v_cvt_pk_bf16_f32 v75, v82, v83
	global_store_dwordx2 v14, v[68:69], s[26:27] offset:0
	global_store_dwordx2 v14, v[70:71], s[26:27] offset:512
	global_store_dwordx2 v14, v[72:73], s[26:27] offset:1024
	global_store_dwordx2 v14, v[74:75], s[26:27] offset:1536
	s_branch .Lln0_exit
.Lln0_exit:
	s_branch .LBB0_142
.LBB0_142:
	s_or_b64 exec, exec, s[0:1]
	s_getreg_b32 s2, hwreg(HW_REG_XCC_ID, 0, 4)
	s_waitcnt vmcnt(0)
	s_barrier
	s_mov_b64 s[0:1], exec
	v_readlane_b32 s4, v252, 14
	v_readlane_b32 s5, v252, 15
	s_and_b64 s[4:5], s[0:1], s[4:5]
	s_mov_b64 exec, s[4:5]
	s_cbranch_execz .LBB0_194
	s_mov_b64 s[4:5], src_shared_base
	v_mov_b32_e32 v0, 0x12200
	v_mov_b32_e32 v1, s5
	s_waitcnt vmcnt(0) expcnt(0) lgkmcnt(0)
	flat_load_dword v2, v[0:1] sc0 sc1
	s_waitcnt vmcnt(0)
	v_mov_b32_e32 v0, 0x12204
	flat_load_dword v0, v[0:1] sc0 sc1
	s_waitcnt vmcnt(0)
	s_and_b32 s18, s2, 15
	s_waitcnt lgkmcnt(0)
	v_cmp_eq_u32_e32 vcc, 0, v2
	s_and_saveexec_b64 s[2:3], vcc
	s_cbranch_execz .LBB0_158
	s_add_u32 s4, s88, 0x1000
	s_addc_u32 s5, s89, 0
	s_add_u32 s6, s88, 0x1100
	s_addc_u32 s7, s89, 0
	s_add_u32 s8, s88, 0x1200
	s_addc_u32 s9, s89, 0
	s_mul_i32 s19, s41, s23
	s_add_u32 s10, s88, 0x1300
	s_mul_i32 s19, s19, s40
	s_addc_u32 s11, s89, 0
	s_mov_b32 s20, 1
	v_mov_b32_e32 v17, 0
	s_branch .LBB0_146
